# attention: next-tile LDS-DMA issued at top of iteration (right after the barrier) instead of after softmax; dtype header comment
# baseline (speedup 1.0000x reference)
.LBB0_2757:
	v_mov_b32_e32 v8, v242
	s_lshl_b32 s8, s4, 7
	s_sub_i32 s14, 0x1fff, s8
	v_ashrrev_i32_e32 v9, 4, v8
	v_add_u32_e32 v2, s80, v9
	v_min_i32_e32 v4, s14, v2
	v_readlane_b32 s4, v255, 11
	v_ashrrev_i32_e32 v5, 31, v4
	s_add_i32 s4, s3, s4
	v_and_b32_e32 v10, 15, v8
	v_lshlrev_b64 v[4:5], 12, v[4:5]
	s_ashr_i32 s5, s4, 31
	v_bitop3_b32 v6, v9, v10, 7 bitop3:0x6c
	v_lshl_add_u64 v[4:5], s[78:79], 0, v[4:5]
	s_lshl_b64 s[4:5], s[4:5], 1
	v_lshl_add_u64 v[4:5], v[4:5], 0, s[4:5]
	v_lshlrev_b32_e32 v2, 4, v6
	s_mov_b32 m0, s97
	v_lshl_add_u64 v[4:5], v[4:5], 0, v[2:3]
	global_load_lds_dwordx4 v[4:5], off
	v_add_u32_e32 v4, s82, v9
	v_bitop3_b32 v6, v4, v10, 7 bitop3:0x6c
	v_min_i32_e32 v4, s14, v4
	v_ashrrev_i32_e32 v5, 31, v4
	v_lshlrev_b64 v[4:5], 12, v[4:5]
	v_lshl_add_u64 v[4:5], s[78:79], 0, v[4:5]
	v_lshl_add_u64 v[4:5], v[4:5], 0, s[4:5]
	v_lshlrev_b32_e32 v6, 4, v6
	v_mov_b32_e32 v7, v3
	v_lshl_add_u64 v[4:5], v[4:5], 0, v[6:7]
	s_add_i32 m0, s83, 0
	s_lshl_b32 s44, s3, 1
	global_load_lds_dwordx4 v[4:5], off
	v_add_u32_e32 v4, s86, v9
	v_min_i32_e32 v4, s14, v4
	v_ashrrev_i32_e32 v5, 31, v4
	v_lshlrev_b64 v[4:5], 12, v[4:5]
	v_lshl_add_u64 v[4:5], s[78:79], 0, v[4:5]
	v_lshl_add_u64 v[4:5], v[4:5], 0, s[4:5]
	v_lshl_add_u64 v[4:5], v[4:5], 0, v[2:3]
	s_add_i32 m0, s87, 0
	v_add_u32_e32 v2, s90, v9
	global_load_lds_dwordx4 v[4:5], off
	v_min_i32_e32 v4, s14, v2
	v_ashrrev_i32_e32 v5, 31, v4
	v_lshlrev_b64 v[4:5], 12, v[4:5]
	v_bitop3_b32 v6, v2, v10, 7 bitop3:0x6c
	v_lshl_add_u64 v[4:5], s[78:79], 0, v[4:5]
	v_lshl_add_u64 v[4:5], v[4:5], 0, s[4:5]
	v_lshlrev_b32_e32 v2, 4, v6
	v_lshl_add_u64 v[4:5], v[4:5], 0, v[2:3]
	v_lshrrev_b32_e32 v2, 2, v8
	v_and_or_b32 v2, v2, 7, s96
	v_min_i32_e32 v6, s14, v2
	s_add_i32 m0, s91, 0
	v_ashrrev_i32_e32 v7, 31, v6
	global_load_lds_dwordx4 v[4:5], off
	v_and_b32_e32 v4, 0xffffffe0, v8
	v_lshlrev_b32_e32 v5, 3, v8
	v_lshlrev_b64 v[6:7], 12, v[6:7]
	v_and_or_b32 v4, v5, 24, v4
	v_lshl_add_u64 v[6:7], s[50:51], 0, v[6:7]
	v_lshl_add_u64 v[6:7], v[6:7], 0, s[44:45]
	v_ashrrev_i32_e32 v5, 31, v4
	v_lshl_add_u64 v[4:5], v[4:5], 1, v[6:7]
	s_mov_b32 m0, s42
	v_lshl_add_u64 v[6:7], v[4:5], 0, s[58:59]
	global_load_lds_dwordx4 v[4:5], off
	s_add_i32 m0, s97, 0x10400
	s_sub_i32 s15, 0x2000, s8
	global_load_lds_dwordx4 v[6:7], off
	v_lshl_add_u64 v[6:7], v[4:5], 0, s[52:53]
	s_add_i32 m0, s97, 0x10800
	v_lshl_add_u64 v[4:5], v[4:5], 0, s[48:49]
	global_load_lds_dwordx4 v[6:7], off
	s_add_i32 m0, s97, 0x10c00
	s_ashr_i32 s16, s15, 6
	global_load_lds_dwordx4 v[4:5], off
	s_waitcnt vmcnt(0)
	s_cmp_lt_i32 s16, 1
	s_waitcnt vmcnt(0) lgkmcnt(0)
	s_barrier
	s_cbranch_scc1 .LBB0_2779
	v_lshlrev_b32_e32 v252, 4, v242
	v_lshlrev_b32_e32 v253, 3, v242
	v_and_b32_e32 v252, 0xc0, v252
	v_and_or_b32 v252, v253, 24, v252
	v_and_b32_e32 v253, 0x100, v253
	v_or_b32_e32 v252, v252, v253
	v_lshlrev_b32_e32 v253, 1, v242
	v_and_b32_e32 v253, 32, v253
	v_or_b32_e32 v252, v252, v253
	v_mov_b32_e32 v253, 0x20000
	ds_read_b32 v253, v253
	v_lshl_add_u32 v200, v242, 5, s32
	ds_read_b128 v[204:207], v200 offset:16
	ds_read_b128 v[200:203], v200
	s_waitcnt lgkmcnt(0)
	s_lshl_b32 s2, s2, 7
	s_add_i32 s2, s2, s46
	s_ashr_i32 s17, s2, 6
	s_add_u32 s2, s78, s4
	s_addc_u32 s3, s79, s5
	v_mov_b32_e32 v16, v3
	v_mov_b32_e32 v17, v3
	s_add_u32 s4, s50, s44
	v_mov_b32_e32 v2, v3
	v_mov_b32_e32 v4, v3
	v_mov_b32_e32 v5, v3
	v_mov_b32_e32 v6, v3
	v_mov_b32_e32 v7, v3
	v_mov_b32_e32 v8, v3
	v_mov_b32_e32 v9, v3
	v_mov_b32_e32 v10, v3
	v_mov_b32_e32 v11, v3
	v_mov_b32_e32 v12, v3
	v_mov_b32_e32 v13, v3
	v_mov_b32_e32 v14, v3
	v_mov_b32_e32 v15, v3
	v_mov_b64_e32 v[128:129], v[16:17]
	v_mov_b64_e32 v[112:113], v[16:17]
	v_mov_b64_e32 v[144:145], v[16:17]
	v_mov_b64_e32 v[96:97], v[16:17]
	v_mov_b64_e32 v[80:81], v[16:17]
	v_mov_b64_e32 v[64:65], v[16:17]
	v_mov_b64_e32 v[48:49], v[16:17]
	v_mov_b64_e32 v[32:33], v[16:17]
	s_addc_u32 s5, s51, 0
	s_add_i32 s18, s47, s8
	s_mov_b32 s19, 0
	v_mov_b32_e32 v251, 0xf149f2ca
	v_mov_b32_e32 v250, 0
	s_mov_b32 s20, 0
	s_mov_b32 s21, 0
	v_mov_b64_e32 v[126:127], v[14:15]
	v_mov_b64_e32 v[124:125], v[12:13]
	v_mov_b64_e32 v[122:123], v[10:11]
	v_mov_b64_e32 v[120:121], v[8:9]
	v_mov_b64_e32 v[118:119], v[6:7]
	v_mov_b64_e32 v[116:117], v[4:5]
	v_mov_b64_e32 v[114:115], v[2:3]
	v_mov_b64_e32 v[110:111], v[14:15]
	v_mov_b64_e32 v[108:109], v[12:13]
	v_mov_b64_e32 v[106:107], v[10:11]
	v_mov_b64_e32 v[104:105], v[8:9]
	v_mov_b64_e32 v[102:103], v[6:7]
	v_mov_b64_e32 v[100:101], v[4:5]
	v_mov_b64_e32 v[98:99], v[2:3]
	v_mov_b64_e32 v[142:143], v[14:15]
	v_mov_b64_e32 v[140:141], v[12:13]
	v_mov_b64_e32 v[138:139], v[10:11]
	v_mov_b64_e32 v[136:137], v[8:9]
	v_mov_b64_e32 v[134:135], v[6:7]
	v_mov_b64_e32 v[132:133], v[4:5]
	v_mov_b64_e32 v[130:131], v[2:3]
	v_mov_b64_e32 v[94:95], v[14:15]
	v_mov_b64_e32 v[92:93], v[12:13]
	v_mov_b64_e32 v[90:91], v[10:11]
	v_mov_b64_e32 v[88:89], v[8:9]
	v_mov_b64_e32 v[86:87], v[6:7]
	v_mov_b64_e32 v[84:85], v[4:5]
	v_mov_b64_e32 v[82:83], v[2:3]
	v_mov_b64_e32 v[78:79], v[14:15]
	v_mov_b64_e32 v[76:77], v[12:13]
	v_mov_b64_e32 v[74:75], v[10:11]
	v_mov_b64_e32 v[72:73], v[8:9]
	v_mov_b64_e32 v[70:71], v[6:7]
	v_mov_b64_e32 v[68:69], v[4:5]
	v_mov_b64_e32 v[66:67], v[2:3]
	v_mov_b64_e32 v[62:63], v[14:15]
	v_mov_b64_e32 v[60:61], v[12:13]
	v_mov_b64_e32 v[58:59], v[10:11]
	v_mov_b64_e32 v[56:57], v[8:9]
	v_mov_b64_e32 v[54:55], v[6:7]
	v_mov_b64_e32 v[52:53], v[4:5]
	v_mov_b64_e32 v[50:51], v[2:3]
	v_mov_b64_e32 v[46:47], v[14:15]
	v_mov_b64_e32 v[44:45], v[12:13]
	v_mov_b64_e32 v[42:43], v[10:11]
	v_mov_b64_e32 v[40:41], v[8:9]
	v_mov_b64_e32 v[38:39], v[6:7]
	v_mov_b64_e32 v[36:37], v[4:5]
	v_mov_b64_e32 v[34:35], v[2:3]
	v_mov_b64_e32 v[30:31], v[14:15]
	v_mov_b64_e32 v[28:29], v[12:13]
	v_mov_b64_e32 v[26:27], v[10:11]
	v_mov_b64_e32 v[24:25], v[8:9]
	v_mov_b64_e32 v[22:23], v[6:7]
	v_mov_b64_e32 v[20:21], v[4:5]
	v_mov_b64_e32 v[18:19], v[2:3]
	s_branch .LBB0_2761
.LBB0_2759:
	v_exp_f32_e32 v2, v4
	s_add_i32 s8, s22, 0
	s_add_i32 s8, s8, 0x10000
	v_add_f32_e32 v8, v2, v209
	v_cvt_pk_bf16_f32 v149, v192, v2
	s_waitcnt lgkmcnt(0)
	v_add_u32_e32 v2, s8, v252
	ds_read_b64_tr_b16 v[150:151], v2 offset:0
	ds_read_b64_tr_b16 v[152:153], v2 offset:0x1000
	ds_read_b64_tr_b16 v[154:155], v2 offset:0x2000
	ds_read_b64_tr_b16 v[156:157], v2 offset:0x3000
	ds_read_b64_tr_b16 v[158:159], v2 offset:0x4000
	ds_read_b64_tr_b16 v[160:161], v2 offset:0x5000
	ds_read_b64_tr_b16 v[162:163], v2 offset:0x6000
	ds_read_b64_tr_b16 v[164:165], v2 offset:0x7000
	v_add_f32_e32 v7, v7, v8
	v_add_f32_e32 v250, v250, v7
	v_cvt_pk_bf16_f32 v4, v194, v195
	v_cvt_pk_bf16_f32 v5, v196, v197
	v_cvt_pk_bf16_f32 v6, v198, v199
	v_cvt_pk_bf16_f32 v7, v200, v201
	v_cvt_pk_bf16_f32 v8, v202, v203
	v_cvt_pk_bf16_f32 v9, v204, v205
	v_cvt_pk_bf16_f32 v10, v206, v207
	v_cvt_pk_bf16_f32 v11, v208, v209
	v_cvt_pk_bf16_f32 v12, v178, v179
	v_cvt_pk_bf16_f32 v13, v180, v181
	v_cvt_pk_bf16_f32 v14, v182, v183
	v_cvt_pk_bf16_f32 v15, v184, v185
	v_cvt_pk_bf16_f32 v146, v186, v187
	v_cvt_pk_bf16_f32 v147, v188, v189
	v_cvt_pk_bf16_f32 v148, v190, v191
	ds_read_b64_tr_b16 v[166:167], v2 offset:0x200
	ds_read_b64_tr_b16 v[168:169], v2 offset:0x1200
	ds_read_b64_tr_b16 v[170:171], v2 offset:0x2200
	ds_read_b64_tr_b16 v[172:173], v2 offset:0x3200
	ds_read_b64_tr_b16 v[174:175], v2 offset:0x4200
	ds_read_b64_tr_b16 v[176:177], v2 offset:0x5200
	ds_read_b64_tr_b16 v[178:179], v2 offset:0x6200
	ds_read_b64_tr_b16 v[180:181], v2 offset:0x7200
	s_waitcnt lgkmcnt(8)
	v_mfma_f32_32x32x16_bf16 v[114:129], v[4:7], v[150:153], v[114:129]
	v_mfma_f32_32x32x16_bf16 v[114:129], v[8:11], v[154:157], v[114:129]
	v_mfma_f32_32x32x16_bf16 v[114:129], v[12:15], v[158:161], v[114:129]
	v_mfma_f32_32x32x16_bf16 v[114:129], v[146:149], v[162:165], v[114:129]
	ds_read_b64_tr_b16 v[150:151], v2 offset:0x400
	ds_read_b64_tr_b16 v[152:153], v2 offset:0x1400
	ds_read_b64_tr_b16 v[154:155], v2 offset:0x2400
	ds_read_b64_tr_b16 v[156:157], v2 offset:0x3400
	ds_read_b64_tr_b16 v[158:159], v2 offset:0x4400
	ds_read_b64_tr_b16 v[160:161], v2 offset:0x5400
	ds_read_b64_tr_b16 v[162:163], v2 offset:0x6400
	ds_read_b64_tr_b16 v[164:165], v2 offset:0x7400
	s_waitcnt lgkmcnt(8)
	v_mfma_f32_32x32x16_bf16 v[98:113], v[4:7], v[166:169], v[98:113]
	v_mfma_f32_32x32x16_bf16 v[98:113], v[8:11], v[170:173], v[98:113]
	v_mfma_f32_32x32x16_bf16 v[98:113], v[12:15], v[174:177], v[98:113]
	v_mfma_f32_32x32x16_bf16 v[98:113], v[146:149], v[178:181], v[98:113]
	ds_read_b64_tr_b16 v[166:167], v2 offset:0x600
	ds_read_b64_tr_b16 v[168:169], v2 offset:0x1600
	ds_read_b64_tr_b16 v[170:171], v2 offset:0x2600
	ds_read_b64_tr_b16 v[172:173], v2 offset:0x3600
	ds_read_b64_tr_b16 v[174:175], v2 offset:0x4600
	ds_read_b64_tr_b16 v[176:177], v2 offset:0x5600
	ds_read_b64_tr_b16 v[178:179], v2 offset:0x6600
	ds_read_b64_tr_b16 v[180:181], v2 offset:0x7600
	s_waitcnt lgkmcnt(8)
	v_mfma_f32_32x32x16_bf16 v[130:145], v[4:7], v[150:153], v[130:145]
	v_mfma_f32_32x32x16_bf16 v[130:145], v[8:11], v[154:157], v[130:145]
	v_mfma_f32_32x32x16_bf16 v[130:145], v[12:15], v[158:161], v[130:145]
	v_mfma_f32_32x32x16_bf16 v[130:145], v[146:149], v[162:165], v[130:145]
	ds_read_b64_tr_b16 v[150:151], v2 offset:0x800
	ds_read_b64_tr_b16 v[152:153], v2 offset:0x1800
	ds_read_b64_tr_b16 v[154:155], v2 offset:0x2800
	ds_read_b64_tr_b16 v[156:157], v2 offset:0x3800
	ds_read_b64_tr_b16 v[158:159], v2 offset:0x4800
	ds_read_b64_tr_b16 v[160:161], v2 offset:0x5800
	ds_read_b64_tr_b16 v[162:163], v2 offset:0x6800
	ds_read_b64_tr_b16 v[164:165], v2 offset:0x7800
	s_waitcnt lgkmcnt(8)
	v_mfma_f32_32x32x16_bf16 v[82:97], v[4:7], v[166:169], v[82:97]
	v_mfma_f32_32x32x16_bf16 v[82:97], v[8:11], v[170:173], v[82:97]
	v_mfma_f32_32x32x16_bf16 v[82:97], v[12:15], v[174:177], v[82:97]
	v_mfma_f32_32x32x16_bf16 v[82:97], v[146:149], v[178:181], v[82:97]
	ds_read_b64_tr_b16 v[166:167], v2 offset:0xa00
	ds_read_b64_tr_b16 v[168:169], v2 offset:0x1a00
	ds_read_b64_tr_b16 v[170:171], v2 offset:0x2a00
	ds_read_b64_tr_b16 v[172:173], v2 offset:0x3a00
	ds_read_b64_tr_b16 v[174:175], v2 offset:0x4a00
	ds_read_b64_tr_b16 v[176:177], v2 offset:0x5a00
	ds_read_b64_tr_b16 v[178:179], v2 offset:0x6a00
	ds_read_b64_tr_b16 v[180:181], v2 offset:0x7a00
	s_waitcnt lgkmcnt(8)
	v_mfma_f32_32x32x16_bf16 v[66:81], v[4:7], v[150:153], v[66:81]
	v_mfma_f32_32x32x16_bf16 v[66:81], v[8:11], v[154:157], v[66:81]
	v_mfma_f32_32x32x16_bf16 v[66:81], v[12:15], v[158:161], v[66:81]
	v_mfma_f32_32x32x16_bf16 v[66:81], v[146:149], v[162:165], v[66:81]
	ds_read_b64_tr_b16 v[150:151], v2 offset:0xc00
	ds_read_b64_tr_b16 v[152:153], v2 offset:0x1c00
	ds_read_b64_tr_b16 v[154:155], v2 offset:0x2c00
	ds_read_b64_tr_b16 v[156:157], v2 offset:0x3c00
	ds_read_b64_tr_b16 v[158:159], v2 offset:0x4c00
	ds_read_b64_tr_b16 v[160:161], v2 offset:0x5c00
	ds_read_b64_tr_b16 v[162:163], v2 offset:0x6c00
	ds_read_b64_tr_b16 v[164:165], v2 offset:0x7c00
	s_waitcnt lgkmcnt(8)
	v_mfma_f32_32x32x16_bf16 v[50:65], v[4:7], v[166:169], v[50:65]
	v_mfma_f32_32x32x16_bf16 v[50:65], v[8:11], v[170:173], v[50:65]
	v_mfma_f32_32x32x16_bf16 v[50:65], v[12:15], v[174:177], v[50:65]
	v_mfma_f32_32x32x16_bf16 v[50:65], v[146:149], v[178:181], v[50:65]
	ds_read_b64_tr_b16 v[166:167], v2 offset:0xe00
	ds_read_b64_tr_b16 v[168:169], v2 offset:0x1e00
	ds_read_b64_tr_b16 v[170:171], v2 offset:0x2e00
	ds_read_b64_tr_b16 v[172:173], v2 offset:0x3e00
	ds_read_b64_tr_b16 v[174:175], v2 offset:0x4e00
	ds_read_b64_tr_b16 v[176:177], v2 offset:0x5e00
	ds_read_b64_tr_b16 v[178:179], v2 offset:0x6e00
	ds_read_b64_tr_b16 v[180:181], v2 offset:0x7e00
	s_waitcnt lgkmcnt(8)
	v_mfma_f32_32x32x16_bf16 v[34:49], v[4:7], v[150:153], v[34:49]
	v_mfma_f32_32x32x16_bf16 v[34:49], v[8:11], v[154:157], v[34:49]
	v_mfma_f32_32x32x16_bf16 v[34:49], v[12:15], v[158:161], v[34:49]
	v_mfma_f32_32x32x16_bf16 v[34:49], v[146:149], v[162:165], v[34:49]
	s_waitcnt lgkmcnt(0)
	v_mfma_f32_32x32x16_bf16 v[18:33], v[4:7], v[166:169], v[18:33]
	v_mfma_f32_32x32x16_bf16 v[18:33], v[8:11], v[170:173], v[18:33]
	v_mfma_f32_32x32x16_bf16 v[18:33], v[12:15], v[174:177], v[18:33]
	v_mfma_f32_32x32x16_bf16 v[18:33], v[146:149], v[178:181], v[18:33]
	v_lshl_add_u32 v200, v242, 5, s32
	ds_read_b128 v[204:207], v200 offset:16
	ds_read_b128 v[200:203], v200

.LBB0_2765:
	s_andn2_b64 vcc, exec, s[8:9]
	s_cbranch_vccnz .LBB0_2775
	s_add_i32 s10, s19, 1
	s_cmp_ge_i32 s10, s16
	s_cbranch_scc1 .Lat_nodma
	s_add_i32 s10, s80, s20
	s_add_i32 s10, s10, 64
	s_lshl_b32 s10, s10, 12
	s_add_u32 s98, s2, s10
	s_addc_u32 s99, s3, 0
	s_add_i32 s8, s21, 0x8000
	s_and_b32 s8, s8, 0x8000
	s_add_i32 s9, s8, 0
	s_add_i32 m0, s9, s81
	s_add_i32 s10, s54, s20
	global_load_lds_dwordx4 v200, s[98:99]
	s_add_i32 m0, s9, s83
	s_lshl_b32 s10, s10, 12
	global_load_lds_dwordx4 v201, s[98:99]
	s_add_i32 m0, s9, s87
	s_add_i32 s8, s42, s8
	global_load_lds_dwordx4 v202, s[98:99]
	s_add_i32 m0, s9, s91
	s_nop 0
	global_load_lds_dwordx4 v203, s[98:99]
	s_add_u32 s98, s4, s10
	s_addc_u32 s99, s5, 0
	s_mov_b32 m0, s8
	s_nop 0
	global_load_lds_dwordx4 v204, s[98:99]
	s_add_i32 m0, s8, 0x400
	s_nop 0
	global_load_lds_dwordx4 v205, s[98:99]
	s_add_i32 m0, s8, 0x800
	s_nop 0
	global_load_lds_dwordx4 v206, s[98:99]
	s_add_i32 m0, s8, 0xc00
	s_nop 0
	global_load_lds_dwordx4 v207, s[98:99]
.Lat_nodma:
	s_and_b32 s22, s21, 0x8000
	v_ashrrev_i32_e32 v16, 5, v242
	v_and_b32_e32 v2, 31, v242
	s_add_i32 s8, s43, s22
	v_lshlrev_b32_e32 v17, 4, v16
	v_lshlrev_b32_e32 v190, 4, v242
	v_and_b32_e32 v190, 0x70, v190
	v_lshl_add_u32 v191, v2, 8, s8
	v_xad_u32 v192, v17, v190, v191
	v_add_u32_e32 v193, 32, v17
	v_xad_u32 v193, v193, v190, v191
	ds_read_b128 v[4:7], v192
	ds_read_b128 v[8:11], v192 offset:8192
	ds_read_b128 v[12:15], v193
	ds_read_b128 v[178:181], v193 offset:8192
	v_add_u32_e32 v194, 64, v17
	v_xad_u32 v194, v194, v190, v191
	ds_read_b128 v[182:185], v194
	ds_read_b128 v[186:189], v194 offset:8192
	v_add_u32_e32 v195, 0x60, v17
	v_xad_u32 v195, v195, v190, v191
	v_add_u32_e32 v196, 0x80, v17
	v_xad_u32 v196, v196, v190, v191
	v_add_u32_e32 v197, 0xa0, v17
	v_xad_u32 v197, v197, v190, v191
	v_add_u32_e32 v198, 0xc0, v17
	v_xad_u32 v198, v198, v190, v191
	v_add_u32_e32 v199, 0xe0, v17
	v_xad_u32 v199, v199, v190, v191
	s_waitcnt lgkmcnt(0)
	v_mfma_f32_32x32x16_bf16 v[162:177], v[4:7], v[210:213], 0
	v_mfma_f32_32x32x16_bf16 v[146:161], v[8:11], v[210:213], 0
	ds_read_b128 v[4:7], v195
	ds_read_b128 v[8:11], v195 offset:8192
	v_mfma_f32_32x32x16_bf16 v[162:177], v[12:15], v[214:217], v[162:177]
	v_mfma_f32_32x32x16_bf16 v[146:161], v[178:181], v[214:217], v[146:161]
	ds_read_b128 v[12:15], v196
	ds_read_b128 v[178:181], v196 offset:8192
	v_mfma_f32_32x32x16_bf16 v[162:177], v[182:185], v[218:221], v[162:177]
	v_mfma_f32_32x32x16_bf16 v[146:161], v[186:189], v[218:221], v[146:161]
	ds_read_b128 v[182:185], v197
	ds_read_b128 v[186:189], v197 offset:8192
	s_waitcnt lgkmcnt(0)
	v_mfma_f32_32x32x16_bf16 v[162:177], v[4:7], v[222:225], v[162:177]
	v_mfma_f32_32x32x16_bf16 v[146:161], v[8:11], v[222:225], v[146:161]
	ds_read_b128 v[4:7], v198
	ds_read_b128 v[8:11], v198 offset:8192
	v_mfma_f32_32x32x16_bf16 v[162:177], v[12:15], v[226:229], v[162:177]
	v_mfma_f32_32x32x16_bf16 v[146:161], v[178:181], v[226:229], v[146:161]
	ds_read_b128 v[12:15], v199
	ds_read_b128 v[178:181], v199 offset:8192
	v_mfma_f32_32x32x16_bf16 v[162:177], v[182:185], v[230:233], v[162:177]
	v_mfma_f32_32x32x16_bf16 v[146:161], v[186:189], v[230:233], v[146:161]
	s_waitcnt lgkmcnt(0)
	v_mfma_f32_32x32x16_bf16 v[162:177], v[4:7], v[234:237], v[162:177]
	v_mfma_f32_32x32x16_bf16 v[146:161], v[8:11], v[234:237], v[146:161]
	v_mfma_f32_32x32x16_bf16 v[162:177], v[12:15], v[238:241], v[162:177]
	v_mfma_f32_32x32x16_bf16 v[146:161], v[178:181], v[238:241], v[146:161]
	s_add_i32 s23, s18, s20
	s_add_i32 s10, s20, 63
	s_add_i32 s8, s23, 0xffffe0bf
	s_cmpk_lt_i32 s8, 0xffa6
	s_cselect_b64 s[8:9], -1, 0
	s_cmp_lt_i32 s10, s15
	s_cselect_b64 s[12:13], -1, 0
	s_and_b64 s[10:11], s[12:13], s[8:9]
	s_mov_b64 s[8:9], -1
	s_and_b64 vcc, exec, s[10:11]
	v_lshlrev_b32_e32 v11, 2, v16
	s_cbranch_vccnz .LBB0_2768
	v_sub_u32_e32 v2, v11, v2
	v_add_u32_e32 v2, s23, v2
	s_add_i32 s23, 0, 0x18600
	v_lshl_add_u32 v2, v2, 2, s23
	ds_read2_b32 v[178:179], v2 offset0:0 offset1:1
	ds_read2_b32 v[180:181], v2 offset0:2 offset1:3
	ds_read2_b32 v[182:183], v2 offset0:8 offset1:9
	ds_read2_b32 v[184:185], v2 offset0:10 offset1:11
	ds_read2_b32 v[186:187], v2 offset0:16 offset1:17
	ds_read2_b32 v[188:189], v2 offset0:18 offset1:19
	ds_read2_b32 v[190:191], v2 offset0:24 offset1:25
	ds_read2_b32 v[192:193], v2 offset0:26 offset1:27
	ds_read2_b32 v[194:195], v2 offset0:32 offset1:33
	ds_read2_b32 v[196:197], v2 offset0:34 offset1:35
	ds_read2_b32 v[198:199], v2 offset0:40 offset1:41
	ds_read2_b32 v[200:201], v2 offset0:42 offset1:43
	ds_read2_b32 v[202:203], v2 offset0:48 offset1:49
	ds_read2_b32 v[204:205], v2 offset0:50 offset1:51
	ds_read2_b32 v[206:207], v2 offset0:56 offset1:57
	ds_read2_b32 v[208:209], v2 offset0:58 offset1:59
	s_waitcnt lgkmcnt(0)
	v_fmamk_f32 v162, v162, 0x3e0293ee, v178
	v_fmamk_f32 v146, v146, 0x3e0293ee, v194
	v_fmamk_f32 v163, v163, 0x3e0293ee, v179
	v_fmamk_f32 v147, v147, 0x3e0293ee, v195
	v_max_f32_e32 v2, v162, v146
	v_fmamk_f32 v164, v164, 0x3e0293ee, v180
	v_fmamk_f32 v148, v148, 0x3e0293ee, v196
	v_max3_f32 v2, v2, v163, v147
	v_fmamk_f32 v165, v165, 0x3e0293ee, v181
	v_fmamk_f32 v149, v149, 0x3e0293ee, v197
	v_max3_f32 v2, v2, v164, v148
	v_fmamk_f32 v166, v166, 0x3e0293ee, v182
	v_fmamk_f32 v150, v150, 0x3e0293ee, v198
	v_max3_f32 v2, v2, v165, v149
	v_fmamk_f32 v167, v167, 0x3e0293ee, v183
	v_fmamk_f32 v151, v151, 0x3e0293ee, v199
	v_max3_f32 v2, v2, v166, v150
	v_fmamk_f32 v168, v168, 0x3e0293ee, v184
	v_fmamk_f32 v152, v152, 0x3e0293ee, v200
	v_max3_f32 v2, v2, v167, v151
	v_fmamk_f32 v169, v169, 0x3e0293ee, v185
	v_fmamk_f32 v153, v153, 0x3e0293ee, v201
	v_max3_f32 v2, v2, v168, v152
	v_fmamk_f32 v170, v170, 0x3e0293ee, v186
	v_fmamk_f32 v154, v154, 0x3e0293ee, v202
	v_max3_f32 v2, v2, v169, v153
	v_fmamk_f32 v171, v171, 0x3e0293ee, v187
	v_fmamk_f32 v155, v155, 0x3e0293ee, v203
	v_max3_f32 v2, v2, v170, v154
	v_fmamk_f32 v172, v172, 0x3e0293ee, v188
	v_fmamk_f32 v156, v156, 0x3e0293ee, v204
	v_max3_f32 v2, v2, v171, v155
	v_fmamk_f32 v173, v173, 0x3e0293ee, v189
	v_fmamk_f32 v157, v157, 0x3e0293ee, v205
	v_max3_f32 v2, v2, v172, v156
	v_fmamk_f32 v174, v174, 0x3e0293ee, v190
	v_fmamk_f32 v158, v158, 0x3e0293ee, v206
	v_max3_f32 v2, v2, v173, v157
	v_fmamk_f32 v175, v175, 0x3e0293ee, v191
	v_fmamk_f32 v159, v159, 0x3e0293ee, v207
	v_max3_f32 v2, v2, v174, v158
	v_fmamk_f32 v176, v176, 0x3e0293ee, v192
	v_fmamk_f32 v160, v160, 0x3e0293ee, v208
	v_max3_f32 v2, v2, v175, v159
	v_fmamk_f32 v177, v177, 0x3e0293ee, v193
	v_fmamk_f32 v161, v161, 0x3e0293ee, v209
	v_max3_f32 v2, v2, v176, v160
	v_max3_f32 v4, v2, v177, v161
	s_mov_b64 s[8:9], 0

.LBB0_2774:
	s_add_i32 s19, s19, 1
	s_branch .LBB0_2759

.LBB0_2777:
	v_sub_f32_e32 v4, v253, v251
	v_fmamk_f32 v2, v162, 0x3e0293ee, v4
	v_exp_f32_e32 v194, v2
	v_fmamk_f32 v2, v146, 0x3e0293ee, v4
	v_exp_f32_e32 v178, v2
	v_fmamk_f32 v2, v163, 0x3e0293ee, v4
	v_exp_f32_e32 v195, v2
	v_fmamk_f32 v2, v147, 0x3e0293ee, v4
	v_exp_f32_e32 v179, v2
	v_fmamk_f32 v2, v164, 0x3e0293ee, v4
	v_exp_f32_e32 v196, v2
	v_fmamk_f32 v2, v148, 0x3e0293ee, v4
	v_exp_f32_e32 v180, v2
	v_fmamk_f32 v2, v165, 0x3e0293ee, v4
	v_exp_f32_e32 v197, v2
	v_fmamk_f32 v2, v149, 0x3e0293ee, v4
	v_exp_f32_e32 v181, v2
	v_pk_add_f32 v[6:7], v[194:195], v[178:179]
	v_fmamk_f32 v2, v166, 0x3e0293ee, v4
	v_exp_f32_e32 v198, v2
	v_fmamk_f32 v2, v150, 0x3e0293ee, v4
	v_exp_f32_e32 v182, v2
	v_fmamk_f32 v2, v167, 0x3e0293ee, v4
	v_exp_f32_e32 v199, v2
	v_fmamk_f32 v2, v151, 0x3e0293ee, v4
	v_exp_f32_e32 v183, v2
	v_pk_add_f32 v[6:7], v[6:7], v[196:197]
	v_pk_add_f32 v[6:7], v[6:7], v[180:181]
	v_fmamk_f32 v2, v168, 0x3e0293ee, v4
	v_exp_f32_e32 v200, v2
	v_fmamk_f32 v2, v152, 0x3e0293ee, v4
	v_exp_f32_e32 v184, v2
	v_fmamk_f32 v2, v169, 0x3e0293ee, v4
	v_exp_f32_e32 v201, v2
	v_fmamk_f32 v2, v153, 0x3e0293ee, v4
	v_exp_f32_e32 v185, v2
	v_pk_add_f32 v[6:7], v[6:7], v[198:199]
	v_pk_add_f32 v[6:7], v[6:7], v[182:183]
	v_fmamk_f32 v2, v170, 0x3e0293ee, v4
	v_exp_f32_e32 v202, v2
	v_fmamk_f32 v2, v154, 0x3e0293ee, v4
	v_exp_f32_e32 v186, v2
	v_fmamk_f32 v2, v171, 0x3e0293ee, v4
	v_exp_f32_e32 v203, v2
	v_fmamk_f32 v2, v155, 0x3e0293ee, v4
	v_exp_f32_e32 v187, v2
	v_pk_add_f32 v[6:7], v[6:7], v[200:201]
	v_pk_add_f32 v[6:7], v[6:7], v[184:185]
	v_fmamk_f32 v2, v172, 0x3e0293ee, v4
	v_exp_f32_e32 v204, v2
	v_fmamk_f32 v2, v156, 0x3e0293ee, v4
	v_exp_f32_e32 v188, v2
	v_fmamk_f32 v2, v173, 0x3e0293ee, v4
	v_exp_f32_e32 v205, v2
	v_fmamk_f32 v2, v157, 0x3e0293ee, v4
	v_exp_f32_e32 v189, v2
	v_pk_add_f32 v[6:7], v[6:7], v[202:203]
	v_pk_add_f32 v[6:7], v[6:7], v[186:187]
	v_fmamk_f32 v2, v174, 0x3e0293ee, v4
	v_exp_f32_e32 v206, v2
	v_fmamk_f32 v2, v158, 0x3e0293ee, v4
	v_exp_f32_e32 v190, v2
	v_fmamk_f32 v2, v175, 0x3e0293ee, v4
	v_exp_f32_e32 v207, v2
	v_fmamk_f32 v2, v159, 0x3e0293ee, v4
	v_exp_f32_e32 v191, v2
	v_pk_add_f32 v[6:7], v[6:7], v[204:205]
	v_pk_add_f32 v[6:7], v[6:7], v[188:189]
	v_fmamk_f32 v2, v176, 0x3e0293ee, v4
	v_exp_f32_e32 v208, v2
	v_fmamk_f32 v2, v160, 0x3e0293ee, v4
	v_exp_f32_e32 v192, v2
	v_fmamk_f32 v2, v177, 0x3e0293ee, v4
	v_exp_f32_e32 v209, v2
	v_pk_add_f32 v[6:7], v[6:7], v[206:207]
	v_pk_add_f32 v[6:7], v[6:7], v[190:191]
	v_fmac_f32_e32 v4, 0x3e0293ee, v161
	v_add_f32_e32 v7, v6, v7
	v_add_f32_e32 v7, v7, v208
	v_add_f32_e32 v7, v7, v192
	s_add_i32 s19, s19, 1
	s_branch .LBB0_2759
